# RG-LRU item start: conv-tap and first-tile loads issued together with one wait (were seven dependent round trips)
# speedup vs baseline: 1.0043x; 1.0043x over previous
.LBB0_995:
	s_bfe_u32 s48, s45, 0x30002
	s_and_b32 s0, s45, 3
	s_lshl_b32 s1, s48, 15
	s_or_b32 s4, s12, s1
	v_lshl_or_b32 v0, s0, 13, v127
	v_lshl_add_u64 v[14:15], v[102:103], 0, s[4:5]
	v_or_b32_e32 v16, 0x1000, v0
	v_mov_b32_e32 v17, v1
	v_lshl_add_u64 v[2:3], v[14:15], 0, v[0:1]
	v_lshl_add_u64 v[6:7], v[14:15], 0, v[16:17]
	v_lshl_add_u64 v[14:15], v[14:15], 0, s[68:69]
	s_lshl_b32 s47, s0, 5
	v_lshl_add_u64 v[26:27], v[14:15], 0, v[0:1]
	s_lshl_b32 s46, s48, 7
	v_or_b32_e32 v0, s47, v122
	v_or_b32_e32 v0, s46, v0
	v_readlane_b32 s80, v246, 26
	v_lshlrev_b64 v[66:67], 2, v[0:1]
	v_readlane_b32 s86, v246, 32
	v_readlane_b32 s87, v246, 33
	v_lshl_add_u64 v[14:15], v[14:15], 0, v[16:17]
	v_readlane_b32 s90, v246, 36
	v_readlane_b32 s91, v246, 37
	v_readlane_b32 s92, v246, 38
	v_readlane_b32 s93, v246, 39
	v_lshl_add_u64 v[68:69], s[86:87], 0, v[66:67]
	global_load_dwordx4 v[30:33], v[2:3], off
	global_load_dwordx4 v[18:21], v[2:3], off offset:64
	global_load_dwordx4 v[10:13], v[2:3], off offset:128
	s_nop 0
	global_load_dwordx4 v[2:5], v[2:3], off offset:192
	s_nop 0
	global_load_dwordx4 v[42:45], v[6:7], off
	global_load_dwordx4 v[34:37], v[6:7], off offset:64
	global_load_dwordx4 v[22:25], v[6:7], off offset:128
	s_nop 0
	global_load_dwordx4 v[6:9], v[6:7], off offset:192
	s_nop 0
	global_load_dwordx4 v[58:61], v[26:27], off
	global_load_dwordx4 v[50:53], v[26:27], off offset:64
	global_load_dwordx4 v[38:41], v[26:27], off offset:128
	s_nop 0
	global_load_dwordx4 v[26:29], v[26:27], off offset:192
	s_nop 0
	global_load_dwordx4 v[62:65], v[14:15], off
	global_load_dwordx4 v[54:57], v[14:15], off offset:64
	global_load_dwordx4 v[46:49], v[14:15], off offset:128
	s_nop 0
	global_load_dwordx4 v[14:17], v[14:15], off offset:192
	v_lshl_add_u64 v[70:71], s[90:91], 0, v[66:67]
	v_lshl_add_u64 v[72:73], s[92:93], 0, v[66:67]
	global_load_dword v136, v[68:69], off
	global_load_dword v134, v[68:69], off offset:64
	global_load_dword v135, v[70:71], off
	global_load_dword v0, v[70:71], off offset:64
	global_load_dword v67, v[72:73], off
	global_load_dword v66, v[72:73], off offset:64
	v_readlane_b32 s81, v246, 27
	v_readlane_b32 s82, v246, 28
	v_readlane_b32 s83, v246, 29
	v_readlane_b32 s84, v246, 30
	v_readlane_b32 s85, v246, 31
	v_readlane_b32 s88, v246, 34
	v_readlane_b32 s89, v246, 35
	v_readlane_b32 s94, v246, 40
	v_readlane_b32 s95, v246, 41
	s_lshl_b32 s0, s45, 6
	s_and_b32 s4, s0, 0xfffff800
	s_lshl_b32 s0, s4, 13
	s_lshl_b32 s1, s48, 8
	s_or_b32 s0, s0, s1
	v_add_u32_e32 v74, s0, v110
	v_add_u32_e32 v75, 0x40000, v74
	v_add_u32_e32 v84, 0x80000, v74
	v_add_u32_e32 v85, 0xc0000, v74
	global_load_dwordx4 v[76:79], v74, s[10:11]
	global_load_dwordx4 v[80:83], v75, s[10:11]
	global_load_dwordx4 v[86:89], v84, s[10:11]
	global_load_dwordx4 v[90:93], v85, s[10:11]
	s_and_saveexec_b64 s[0:1], s[14:15]
	s_cbranch_execz .LBB0_997
	s_lshl_b32 s4, s46, 2
	v_lshl_add_u64 v[68:69], v[104:105], 0, s[4:5]
	v_add_co_u32_e32 v70, vcc, 0x1000, v68
	global_load_dword v72, v[68:69], off
	s_nop 0
	v_addc_co_u32_e32 v71, vcc, 0, v69, vcc
	global_load_dword v94, v[70:71], off
	v_readlane_b32 s80, v246, 26
	v_readlane_b32 s82, v246, 28
	v_readlane_b32 s83, v246, 29
	v_readlane_b32 s81, v246, 27
	v_readlane_b32 s84, v246, 30
	v_readlane_b32 s85, v246, 31
	v_readlane_b32 s86, v246, 32
	v_readlane_b32 s87, v246, 33
	v_readlane_b32 s88, v246, 34
	v_readlane_b32 s89, v246, 35
	v_readlane_b32 s90, v246, 36
	v_readlane_b32 s91, v246, 37
	v_readlane_b32 s92, v246, 38
	v_readlane_b32 s93, v246, 39
	v_readlane_b32 s94, v246, 40
	v_readlane_b32 s95, v246, 41
	v_add_co_u32_e32 v96, vcc, 0x2000, v68
	s_nop 1
	v_addc_co_u32_e32 v97, vcc, 0, v69, vcc
	v_add_co_u32_e32 v98, vcc, 0x3000, v68
	global_load_dword v95, v[96:97], off
	s_nop 0
	v_addc_co_u32_e32 v99, vcc, 0, v69, vcc
	global_load_dword v106, v[98:99], off
	v_add_u32_e32 v100, s46, v114
	v_ashrrev_i32_e32 v101, 31, v100
	v_lshl_add_u64 v[100:101], v[100:101], 2, s[82:83]
	global_load_dword v107, v[100:101], off
	s_waitcnt vmcnt(0)
	ds_write2st64_b32 v113, v72, v94 offset1:2
	ds_write2st64_b32 v113, v95, v106 offset0:4 offset1:6
	ds_write_b32 v113, v107 offset:2048
.LBB0_997:
	s_or_b64 exec, exec, s[0:1]
	s_lshl_b32 s0, s45, 6
	s_and_b32 s4, s0, 0xfffff800
	s_lshl_b32 s0, s4, 13
	s_lshl_b32 s1, s48, 8
	s_or_b32 s0, s0, s1
	v_add_u32_e32 v68, v111, v115
	s_waitcnt vmcnt(0)
	ds_write_b128 v68, v[76:79] offset:768
	ds_write_b128 v68, v[80:83] offset:8960
	ds_write_b128 v68, v[86:89] offset:17152
	ds_write_b128 v68, v[90:93] offset:25344
	s_and_saveexec_b64 s[0:1], s[16:17]
	s_cbranch_execz .LBB0_999
	v_mov_b32_e32 v70, v1
	s_nop 0
	v_mov_b32_e32 v71, v70
	v_mov_b32_e32 v72, v70
	v_mov_b32_e32 v73, v70
	ds_write_b128 v68, v[70:73]
